# dynamic weight conversion: workgroup claims blocks of 16 items (two per wave, one atomic claim per two items)
# baseline (speedup 1.0000x reference)
.Lmy_cv5_w:
	s_barrier
	v_mov_b32_e32 v90, 0x21008
	ds_read_b32 v90, v90
	s_waitcnt lgkmcnt(0)
	s_barrier
	v_readfirstlane_b32 s12, v90
	v_readfirstlane_b32 s100, v237
	s_lshr_b32 s100, s100, 6
	s_lshl_b32 s12, s12, 4
	s_add_i32 s12, s12, s100
	s_load_dwordx2 s[6:7], s[0:1], 0x80
	s_add_i32 s4, s56, 1
	s_lshl_b32 s5, s5, 14
	s_add_i32 s13, s5, 0
	s_lshr_b32 s42, s4, 1
	s_lshl_b32 s4, s4, 12
	s_waitcnt lgkmcnt(0)
	s_add_u32 s6, s6, s4
	v_and_b32_e32 v36, 63, v37
	s_addc_u32 s7, s7, 0
	s_andn2_b64 vcc, exec, s[58:59]
	s_mov_b64 s[4:5], -1
	s_cbranch_vccnz .LBB0_301
	s_load_dwordx2 s[8:9], s[0:1], 0x8
	s_mul_i32 s5, s42, 0x600000
	s_mul_hi_u32 s4, s42, 0x600000
	s_waitcnt lgkmcnt(0)
	s_add_u32 s14, s8, s5
	s_addc_u32 s15, s9, s4
	s_load_dwordx2 s[8:9], s[0:1], 0x20
	s_lshl_b64 s[4:5], s[42:43], 22
	s_waitcnt lgkmcnt(0)
	s_add_u32 s16, s8, s4
	s_addc_u32 s17, s9, s5
	s_cmpk_lt_i32 s12, 0x500
	s_cselect_b64 s[8:9], -1, 0
	s_cmpk_gt_i32 s12, 0x4ff
	s_cbranch_scc1 .LBB0_231
	s_cmpk_gt_i32 s12, 0x2ff
	s_cselect_b64 s[4:5], -1, 0
	s_and_b64 s[10:11], s[4:5], exec
	s_movk_i32 s10, 0x600
	s_cselect_b32 s18, 0x400, s10
	s_cselect_b32 s20, 0xfffffd00, 0
	s_lshr_b32 s19, s18, 5
	s_abs_i32 s10, s19
	v_cvt_f32_u32_e32 v0, s10
	s_sub_i32 s22, 0, s10
	s_add_i32 s20, s20, s12
	s_abs_i32 s21, s20
	v_rcp_iflag_f32_e32 v0, v0
	s_xor_b32 s11, s20, s19
	s_ashr_i32 s11, s11, 31
	v_lshrrev_b32_e32 v2, 5, v36
	v_mul_f32_e32 v0, 0x4f7ffffe, v0
	v_cvt_u32_f32_e32 v0, v0
	v_mov_b32_e32 v8, 1.0
	v_readfirstlane_b32 s23, v0
	s_mul_i32 s22, s22, s23
	s_mul_hi_u32 s22, s23, s22
	s_add_i32 s23, s23, s22
	s_mul_hi_u32 s22, s21, s23
	s_mul_i32 s23, s22, s10
	s_sub_i32 s21, s21, s23
	s_add_i32 s24, s22, 1
	s_sub_i32 s23, s21, s10
	s_cmp_ge_u32 s21, s10
	s_cselect_b32 s22, s24, s22
	s_cselect_b32 s21, s23, s21
	s_add_i32 s23, s22, 1
	s_cmp_ge_u32 s21, s10
	s_cselect_b32 s10, s23, s22
	s_xor_b32 s10, s10, s11
	s_sub_i32 s21, s10, s11
	v_lshl_or_b32 v2, s21, 6, v2
	s_or_b64 s[10:11], s[4:5], s[92:93]
	v_ashrrev_i32_e32 v3, 31, v2
	s_and_b64 vcc, exec, s[10:11]
	v_lshl_add_u64 v[6:7], v[2:3], 2, s[6:7]
	v_mov_b32_e32 v3, 1.0
	s_cbranch_vccnz .LBB0_168
	global_load_dword v3, v[6:7], off

.LBB0_235:
	v_add_u32_e32 v35, 0x400, v44
	ds_write2_b32 v44, v2, v3 offset1:66
	ds_write2_b32 v44, v4, v5 offset0:132 offset1:198
	ds_write2_b32 v35, v6, v7 offset0:8 offset1:74
	ds_write2_b32 v35, v8, v9 offset0:140 offset1:206
	v_add_u32_e32 v35, 0x800, v44
	ds_write2_b32 v35, v10, v11 offset0:16 offset1:82
	ds_write2_b32 v35, v12, v13 offset0:148 offset1:214
	v_add_u32_e32 v35, 0xc00, v44
	s_add_i32 s18, s19, 8
	s_bitcmp0_b32 s19, 3
	s_cbranch_scc1 .Lmy_cv4_d
	v_readfirstlane_b32 s100, v237
	s_cmp_gt_u32 s100, 63
	s_cbranch_scc1 .Lmy_cv4_w
	s_mov_b64 s[44:45], exec
	s_mov_b64 exec, 1
	s_lshl_b32 s100, s40, 8
	s_add_i32 s100, s100, 0x5000
	v_mov_b32_e32 v90, s100
	v_mov_b32_e32 v91, 1
	global_atomic_add v91, v90, v91, s[36:37] sc0
	v_mov_b32_e32 v90, 0x21008
	s_waitcnt vmcnt(0)
	ds_write_b32 v90, v91
	s_waitcnt lgkmcnt(0)
	s_mov_b64 exec, s[44:45]
.Lmy_cv4_w:
	s_barrier
	v_mov_b32_e32 v90, 0x21008
	ds_read_b32 v90, v90
	s_waitcnt lgkmcnt(0)
	s_barrier
	v_readfirstlane_b32 s18, v90
	v_readfirstlane_b32 s100, v237
	s_lshr_b32 s100, s100, 6
	s_lshl_b32 s18, s18, 4
	s_add_i32 s18, s18, s100
.Lmy_cv4_d:
	ds_write2_b32 v35, v14, v15 offset0:24 offset1:90
	ds_write2_b32 v35, v16, v17 offset0:156 offset1:222
	v_add_u32_e32 v35, 0x1000, v44
	ds_write2_b32 v35, v18, v19 offset0:32 offset1:98
	ds_write2_b32 v35, v20, v21 offset0:164 offset1:230
	v_add_u32_e32 v35, 0x1400, v44
	s_cmpk_gt_i32 s18, 0x4ff
	ds_write2_b32 v35, v22, v23 offset0:40 offset1:106
	ds_write2_b32 v35, v24, v25 offset0:172 offset1:238
	v_add_u32_e32 v35, 0x1800, v44
	s_cselect_b64 s[8:9], -1, 0
	ds_write2_b32 v35, v26, v27 offset0:48 offset1:114
	ds_write2_b32 v35, v28, v29 offset0:180 offset1:246
	v_add_u32_e32 v35, 0x1c00, v44
	s_and_b64 vcc, exec, s[8:9]
	ds_write2_b32 v35, v30, v31 offset0:56 offset1:122
	ds_write2_b32 v35, v32, v33 offset0:188 offset1:254
	s_cbranch_vccnz .LBB0_234
	s_cmpk_gt_i32 s18, 0x2ff
	s_cselect_b64 s[4:5], -1, 0
	s_and_b64 s[10:11], s[4:5], exec
	s_movk_i32 s10, 0x600
	s_cselect_b32 s20, 0x400, s10
	s_cselect_b32 s10, 0xfffffd00, 0
	s_lshr_b32 s21, s20, 5
	s_abs_i32 s11, s21
	v_cvt_f32_u32_e32 v2, s11
	s_sub_i32 s24, 0, s11
	s_add_i32 s22, s18, s10
	v_rcp_iflag_f32_e32 v2, v2
	s_abs_i32 s23, s22
	s_xor_b32 s10, s22, s21
	s_ashr_i32 s10, s10, 31
	v_mul_f32_e32 v2, 0x4f7ffffe, v2
	v_cvt_u32_f32_e32 v2, v2
	v_mov_b32_e32 v8, 1.0
	v_readfirstlane_b32 s25, v2
	s_mul_i32 s24, s24, s25
	s_mul_hi_u32 s24, s25, s24
	s_add_i32 s25, s25, s24
	s_mul_hi_u32 s24, s23, s25
	s_mul_i32 s25, s24, s11
	s_sub_i32 s23, s23, s25
	s_add_i32 s26, s24, 1
	s_sub_i32 s25, s23, s11
	s_cmp_ge_u32 s23, s11
	s_cselect_b32 s24, s26, s24
	s_cselect_b32 s23, s25, s23
	s_add_i32 s25, s24, 1
	s_cmp_ge_u32 s23, s11
	s_cselect_b32 s11, s25, s24
	s_xor_b32 s11, s11, s10
	s_sub_i32 s23, s11, s10
	v_lshl_or_b32 v2, s23, 6, v38
	s_or_b64 s[10:11], s[4:5], s[92:93]
	v_ashrrev_i32_e32 v3, 31, v2
	s_and_b64 vcc, exec, s[10:11]
	v_lshl_add_u64 v[6:7], v[2:3], 2, s[6:7]
	v_mov_b32_e32 v3, 1.0
	s_cbranch_vccnz .LBB0_238
	global_load_dword v3, v[6:7], off

.LBB0_372:
	v_add_u32_e32 v35, 0x400, v43
	ds_write2_b32 v43, v2, v3 offset1:66
	ds_write2_b32 v43, v4, v5 offset0:132 offset1:198
	ds_write2_b32 v35, v6, v7 offset0:8 offset1:74
	ds_write2_b32 v35, v8, v9 offset0:140 offset1:206
	v_add_u32_e32 v35, 0x800, v43
	ds_write2_b32 v35, v10, v11 offset0:16 offset1:82
	ds_write2_b32 v35, v12, v13 offset0:148 offset1:214
	v_add_u32_e32 v35, 0xc00, v43
	s_add_i32 s13, s18, 8
	s_bitcmp0_b32 s18, 3
	s_cbranch_scc1 .Lmy_cv3_d
	v_readfirstlane_b32 s100, v237
	s_cmp_gt_u32 s100, 63
	s_cbranch_scc1 .Lmy_cv3_w
	s_mov_b64 s[44:45], exec
	s_mov_b64 exec, 1
	s_lshl_b32 s100, s40, 8
	s_add_i32 s100, s100, 0x5000
	v_mov_b32_e32 v90, s100
	v_mov_b32_e32 v91, 1
	global_atomic_add v91, v90, v91, s[36:37] sc0
	v_mov_b32_e32 v90, 0x21008
	s_waitcnt vmcnt(0)
	ds_write_b32 v90, v91
	s_waitcnt lgkmcnt(0)
	s_mov_b64 exec, s[44:45]
.Lmy_cv3_w:
	s_barrier
	v_mov_b32_e32 v90, 0x21008
	ds_read_b32 v90, v90
	s_waitcnt lgkmcnt(0)
	s_barrier
	v_readfirstlane_b32 s13, v90
	v_readfirstlane_b32 s100, v237
	s_lshr_b32 s100, s100, 6
	s_lshl_b32 s13, s13, 4
	s_add_i32 s13, s13, s100
.Lmy_cv3_d:
	ds_write2_b32 v35, v14, v15 offset0:24 offset1:90
	ds_write2_b32 v35, v16, v17 offset0:156 offset1:222
	v_add_u32_e32 v35, 0x1000, v43
	ds_write2_b32 v35, v18, v19 offset0:32 offset1:98
	ds_write2_b32 v35, v20, v21 offset0:164 offset1:230
	v_add_u32_e32 v35, 0x1400, v43
	s_cmpk_gt_i32 s13, 0x11ff
	ds_write2_b32 v35, v22, v23 offset0:40 offset1:106
	ds_write2_b32 v35, v24, v25 offset0:172 offset1:238
	v_add_u32_e32 v35, 0x1800, v43
	s_cselect_b64 s[8:9], -1, 0
	ds_write2_b32 v35, v26, v27 offset0:48 offset1:114
	ds_write2_b32 v35, v28, v29 offset0:180 offset1:246
	v_add_u32_e32 v35, 0x1c00, v43
	s_and_b64 vcc, exec, s[8:9]
	ds_write2_b32 v35, v30, v31 offset0:56 offset1:122
	ds_write2_b32 v35, v32, v33 offset0:188 offset1:254
	s_cbranch_vccnz .LBB0_371
	s_cmpk_gt_i32 s13, 0xbff
	s_cselect_b64 s[4:5], -1, 0
	s_and_b64 s[10:11], s[4:5], exec
	s_cselect_b32 s19, 0x400, s85
	s_cselect_b32 s10, 0xfffff400, 0
	s_lshr_b32 s20, s19, 5
	s_abs_i32 s11, s20
	v_cvt_f32_u32_e32 v2, s11
	s_sub_i32 s23, 0, s11
	s_add_i32 s21, s13, s10
	v_rcp_iflag_f32_e32 v2, v2
	s_abs_i32 s22, s21
	s_xor_b32 s10, s21, s20
	s_ashr_i32 s10, s10, 31
	v_mul_f32_e32 v2, 0x4f7ffffe, v2
	v_cvt_u32_f32_e32 v2, v2
	v_mov_b32_e32 v8, 1.0
	v_readfirstlane_b32 s24, v2
	s_mul_i32 s23, s23, s24
	s_mul_hi_u32 s23, s24, s23
	s_add_i32 s24, s24, s23
	s_mul_hi_u32 s23, s22, s24
	s_mul_i32 s24, s23, s11
	s_sub_i32 s22, s22, s24
	s_add_i32 s25, s23, 1
	s_sub_i32 s24, s22, s11
	s_cmp_ge_u32 s22, s11
	s_cselect_b32 s23, s25, s23
	s_cselect_b32 s22, s24, s22
	s_add_i32 s24, s23, 1
	s_cmp_ge_u32 s22, s11
	s_cselect_b32 s11, s24, s23
	s_xor_b32 s11, s11, s10
	s_sub_i32 s22, s11, s10
	v_lshl_or_b32 v2, s22, 6, v38
	s_or_b64 s[10:11], s[4:5], s[92:93]
	v_ashrrev_i32_e32 v3, 31, v2
	s_and_b64 vcc, exec, s[10:11]
	v_lshl_add_u64 v[6:7], v[2:3], 2, s[6:7]
	v_mov_b32_e32 v3, 1.0
	s_cbranch_vccnz .LBB0_375
	global_load_dword v3, v[6:7], off

.Lmy_cv2_w:
	s_barrier
	v_mov_b32_e32 v90, 0x21008
	ds_read_b32 v90, v90
	s_waitcnt lgkmcnt(0)
	s_barrier
	v_readfirstlane_b32 s18, v90
	v_readfirstlane_b32 s100, v237
	s_lshr_b32 s100, s100, 6
	s_lshl_b32 s18, s18, 4
	s_add_i32 s18, s18, s100
	s_load_dwordx2 s[4:5], s[0:1], 0x60
	s_load_dwordx2 s[10:11], s[0:1], 0x78
	s_load_dwordx2 s[8:9], s[0:1], 0x90
	s_mov_b32 s57, s43
	s_mul_hi_u32 s6, s56, 0x1600000
	v_and_b32_e32 v34, 63, v35
	s_waitcnt lgkmcnt(0)
	s_add_u32 s14, s4, s7
	s_addc_u32 s15, s5, s6
	s_lshl_b64 s[4:5], s[56:57], 12
	s_add_u32 s6, s8, s4
	s_addc_u32 s7, s9, s5
	s_mul_i32 s5, s56, 0xb00000
	s_mul_hi_u32 s4, s56, 0xb00000
	s_add_u32 s16, s10, s5
	s_addc_u32 s17, s11, s4
	s_cmpk_lt_i32 s18, 0x1080
	s_cselect_b64 s[10:11], -1, 0
	s_cmpk_gt_i32 s18, 0x107f
	v_lshrrev_b32_e32 v36, 5, v34
	s_cbranch_scc1 .LBB0_609
	s_cmpk_gt_i32 s18, 0xaff
	s_cselect_b64 s[4:5], -1, 0
	s_and_b64 s[12:13], s[4:5], exec
	s_cselect_b32 s20, 0x400, s3
	s_cselect_b32 s22, 0xfffff500, 0
	s_lshr_b32 s21, s20, 5
	s_abs_i32 s12, s21
	v_cvt_f32_u32_e32 v0, s12
	s_sub_i32 s24, 0, s12
	s_add_i32 s22, s22, s18
	s_abs_i32 s23, s22
	v_rcp_iflag_f32_e32 v0, v0
	s_xor_b32 s13, s22, s21
	s_ashr_i32 s13, s13, 31
	v_mov_b32_e32 v8, 1.0
	v_mul_f32_e32 v0, 0x4f7ffffe, v0
	v_cvt_u32_f32_e32 v0, v0
	s_nop 0
	v_readfirstlane_b32 s25, v0
	s_mul_i32 s24, s24, s25
	s_mul_hi_u32 s24, s25, s24
	s_add_i32 s25, s25, s24
	s_mul_hi_u32 s24, s23, s25
	s_mul_i32 s25, s24, s12
	s_sub_i32 s23, s23, s25
	s_add_i32 s26, s24, 1
	s_sub_i32 s25, s23, s12
	s_cmp_ge_u32 s23, s12
	s_cselect_b32 s24, s26, s24
	s_cselect_b32 s23, s25, s23
	s_add_i32 s25, s24, 1
	s_cmp_ge_u32 s23, s12
	s_cselect_b32 s12, s25, s24
	s_xor_b32 s12, s12, s13
	s_sub_i32 s23, s12, s13
	s_cmp_eq_u64 s[8:9], 0
	v_lshl_or_b32 v2, s23, 6, v36
	s_cselect_b64 s[12:13], -1, 0
	s_or_b64 s[12:13], s[4:5], s[12:13]
	v_ashrrev_i32_e32 v3, 31, v2
	s_and_b64 vcc, exec, s[12:13]
	v_lshl_add_u64 v[6:7], v[2:3], 2, s[6:7]
	v_mov_b32_e32 v3, 1.0
	s_cbranch_vccnz .LBB0_546
	global_load_dword v3, v[6:7], off

.LBB0_612:
	v_add_u32_e32 v35, 0x400, v42
	ds_write2_b32 v42, v2, v3 offset1:66
	ds_write2_b32 v42, v4, v5 offset0:132 offset1:198
	ds_write2_b32 v35, v6, v7 offset0:8 offset1:74
	ds_write2_b32 v35, v8, v9 offset0:140 offset1:206
	v_add_u32_e32 v35, 0x800, v42
	ds_write2_b32 v35, v10, v11 offset0:16 offset1:82
	ds_write2_b32 v35, v12, v13 offset0:148 offset1:214
	v_add_u32_e32 v35, 0xc00, v42
	s_add_i32 s19, s18, 8
	s_bitcmp0_b32 s18, 3
	s_cbranch_scc1 .Lmy_cv1_d
	v_readfirstlane_b32 s100, v237
	s_cmp_gt_u32 s100, 63
	s_cbranch_scc1 .Lmy_cv1_w
	s_mov_b64 s[44:45], exec
	s_mov_b64 exec, 1
	s_lshl_b32 s100, s40, 8
	s_add_i32 s100, s100, 0x5000
	v_mov_b32_e32 v90, s100
	v_mov_b32_e32 v91, 1
	global_atomic_add v91, v90, v91, s[36:37] sc0
	v_mov_b32_e32 v90, 0x21008
	s_waitcnt vmcnt(0)
	ds_write_b32 v90, v91
	s_waitcnt lgkmcnt(0)
	s_mov_b64 exec, s[44:45]
.Lmy_cv1_w:
	s_barrier
	v_mov_b32_e32 v90, 0x21008
	ds_read_b32 v90, v90
	s_waitcnt lgkmcnt(0)
	s_barrier
	v_readfirstlane_b32 s19, v90
	v_readfirstlane_b32 s100, v237
	s_lshr_b32 s100, s100, 6
	s_lshl_b32 s19, s19, 4
	s_add_i32 s19, s19, s100
.Lmy_cv1_d:
	ds_write2_b32 v35, v14, v15 offset0:24 offset1:90
	ds_write2_b32 v35, v16, v17 offset0:156 offset1:222
	v_add_u32_e32 v35, 0x1000, v42
	ds_write2_b32 v35, v18, v19 offset0:32 offset1:98
	ds_write2_b32 v35, v20, v21 offset0:164 offset1:230
	v_add_u32_e32 v35, 0x1400, v42
	s_cmpk_gt_i32 s19, 0x107f
	ds_write2_b32 v35, v22, v23 offset0:40 offset1:106
	ds_write2_b32 v35, v24, v25 offset0:172 offset1:238
	v_add_u32_e32 v35, 0x1800, v42
	s_cselect_b64 s[10:11], -1, 0
	ds_write2_b32 v35, v26, v27 offset0:48 offset1:114
	ds_write2_b32 v35, v28, v29 offset0:180 offset1:246
	v_add_u32_e32 v35, 0x1c00, v42
	s_and_b64 vcc, exec, s[10:11]
	ds_write2_b32 v35, v30, v31 offset0:56 offset1:122
	ds_write2_b32 v35, v32, v33 offset0:188 offset1:254
	s_cbranch_vccnz .LBB0_678
	s_cmpk_gt_i32 s19, 0xaff
	s_cselect_b64 s[4:5], -1, 0
	s_and_b64 s[12:13], s[4:5], exec
	s_cselect_b32 s20, 0x400, s3
	s_cselect_b32 s12, 0xfffff500, 0
	s_lshr_b32 s21, s20, 5
	s_abs_i32 s13, s21
	v_cvt_f32_u32_e32 v2, s13
	s_sub_i32 s24, 0, s13
	s_add_i32 s22, s19, s12
	v_rcp_iflag_f32_e32 v2, v2
	s_abs_i32 s23, s22
	s_xor_b32 s12, s22, s21
	s_ashr_i32 s12, s12, 31
	v_mul_f32_e32 v2, 0x4f7ffffe, v2
	v_cvt_u32_f32_e32 v2, v2
	v_mov_b32_e32 v8, 1.0
	v_readfirstlane_b32 s25, v2
	s_mul_i32 s24, s24, s25
	s_mul_hi_u32 s24, s25, s24
	s_add_i32 s25, s25, s24
	s_mul_hi_u32 s24, s23, s25
	s_mul_i32 s25, s24, s13
	s_sub_i32 s23, s23, s25
	s_add_i32 s26, s24, 1
	s_sub_i32 s25, s23, s13
	s_cmp_ge_u32 s23, s13
	s_cselect_b32 s24, s26, s24
	s_cselect_b32 s23, s25, s23
	s_add_i32 s25, s24, 1
	s_cmp_ge_u32 s23, s13
	s_cselect_b32 s13, s25, s24
	s_xor_b32 s13, s13, s12
	s_sub_i32 s23, s13, s12
	v_lshl_or_b32 v2, s23, 6, v36
	s_or_b64 s[12:13], s[4:5], s[8:9]
	v_ashrrev_i32_e32 v3, 31, v2
	s_and_b64 vcc, exec, s[12:13]
	v_lshl_add_u64 v[6:7], v[2:3], 2, s[6:7]
	v_mov_b32_e32 v3, 1.0
	s_cbranch_vccnz .LBB0_615
	global_load_dword v3, v[6:7], off
